# stack8 + static s_setprio 1 for waves 4-7 across the MD attention/retention phase
# baseline (speedup 1.0000x reference)
; __device__ __forceinline__ unsigned pk2(float lo, float hi) { return pg8::cvt_pk_bf16(lo, hi); }
; __global__ void __launch_bounds__(NTHR, 2) mk_fwd(Args args) {
;     ...
;         if (PH_ON) { PH_FRAME();
;             for (int i = P.vcu * NTHR + P.tid; i < SEQ * 64; i += P.G * NTHR) { const int t = i >> 6, c = i & 63; float sum = 0.f;
; #pragma unroll
;                 for (int ks = 0; ks < 8; ++ks) sum += P_NYQP[(size_t)ks * SEQ * 64 + i];
;                 P_YF[((size_t)(c >> 2) * SEQ + t) * 512 + (c & 3) * 128 + 64] = (bf16)(pk2(sum * (1.0f / 512.0f), 0.f) & 0xffffu); }
.LBB0_988:
	s_or_b64 exec, exec, s[0:1]
	v_mov_b32_e32 v6, v0
	v_readlane_b32 s41, v254, 4
	v_readlane_b32 s81, v254, 6
	v_readlane_b32 s0, v254, 5
	s_waitcnt lgkmcnt(0)
	s_barrier
	v_readfirstlane_b32 s100, v0
	s_nop 3
	s_lshr_b32 s100, s100, 8
	s_cmp_eq_u32 s100, 0
	s_cbranch_scc1 .Lmd_prio_done
	s_setprio 1
.Lmd_prio_done:
	s_mov_b32 s0, s17
	s_ashr_i32 s1, s0, 31
	v_readlane_b32 s2, v254, 7
	v_readlane_b32 s3, v254, 8
	s_add_u32 s13, s2, s0
	v_lshl_add_u32 v2, s81, 9, v6
	s_addc_u32 s16, s3, s1
	v_cmp_gt_i32_e32 vcc, s95, v2
	s_and_saveexec_b64 s[2:3], vcc
	s_cbranch_execz .LBB0_991
	s_add_u32 s4, s13, 0x49e00080
	s_addc_u32 s5, s16, 0
	s_lshl_b32 s6, s41, 9
	v_readlane_b32 s7, v254, 16
	s_add_u32 s8, s7, s0
	v_readlane_b32 s7, v254, 17
	v_ashrrev_i32_e32 v3, 31, v2
	s_addc_u32 s9, s7, s1
	v_lshl_add_u64 v[4:5], v[2:3], 2, s[8:9]
	s_ashr_i32 s7, s6, 31
	v_lshlrev_b32_e32 v3, 9, v6
	v_lshlrev_b32_e32 v6, 7, v6
	s_lshl_b64 s[8:9], s[6:7], 2
	v_lshl_add_u32 v3, s81, 18, v3
	s_lshl_b32 s7, s41, 18
	v_lshl_add_u32 v6, s81, 16, v6
	s_lshl_b32 s12, s41, 16
	s_mov_b64 s[10:11], 0
